# att_phase P.V chains dt=1..3: transposed LDS reads issued 6-8 ahead through a register ring with counted lgkmcnt, alternating accumulators
# speedup vs baseline: 1.0501x; 1.0058x over previous
.LBB0_278:
	s_mov_b32 s12, 0xff61b1e6
	v_max3_f32 v70, v181, s12, v180
	v_max3_f32 v70, v70, v128, v68
	v_max3_f32 v70, v70, v110, v111
	v_max3_f32 v70, v70, v64, v65
	v_max3_f32 v70, v70, v108, v109
	v_max3_f32 v70, v70, v66, v67
	v_max3_f32 v70, v70, v178, v179
	v_max3_f32 v70, v70, v176, v177
	v_max3_f32 v70, v70, v182, v183
	v_max3_f32 v70, v70, v184, v185
	v_max3_f32 v70, v70, v186, v187
	v_max3_f32 v70, v70, v188, v189
	v_max3_f32 v70, v70, v190, v191
	v_max3_f32 v70, v70, v192, v193
	v_max3_f32 v70, v70, v194, v195
	v_max3_f32 v70, v70, v196, v197
	s_sub_i32 s12, 4, s28
	v_or_b32_e32 v102, s34, v222
	s_lshl_b32 s13, s14, 12
	s_lshr_b32 s12, s15, s12
	v_add_u32_e32 v135, s24, v102
	v_max3_f32 v70, v70, v159, v167
	s_or_b32 s36, s12, s13
	v_lshlrev_b32_e32 v135, s28, v135
	v_max3_f32 v70, v70, v163, v106
	v_add_u32_e32 v198, s36, v135
	ds_bpermute_b32 v135, v224, v70
	s_lshl_b32 s96, s1, 15
	v_ashrrev_i32_e32 v199, 31, v198
	s_lshl_b32 s12, s0, 6
	s_ashr_i32 s13, s12, 31
	s_waitcnt lgkmcnt(0)
	v_max_f32_e32 v135, v135, v135
	v_max_f32_e32 v70, v70, v135
	ds_bpermute_b32 v135, v225, v70
	s_ashr_i32 s1, s0, 31
	s_waitcnt lgkmcnt(0)
	v_max_f32_e32 v135, v135, v135
	v_max_f32_e32 v70, v70, v135
	v_sub_f32_e32 v135, v181, v70
	v_exp_f32_e32 v135, v135
	v_sub_f32_e32 v180, v180, v70
	v_exp_f32_e32 v180, v180
	v_sub_f32_e32 v128, v128, v70
	v_exp_f32_e32 v128, v128
	v_sub_f32_e32 v68, v68, v70
	v_exp_f32_e32 v68, v68
	v_add_f32_e32 v171, 0, v135
	v_add_f32_e32 v171, v180, v171
	v_add_f32_e32 v171, v128, v171
	v_add_f32_e32 v171, v68, v171
	v_cvt_pk_bf16_f32 v181, v128, v68
	v_sub_f32_e32 v68, v110, v70
	v_exp_f32_e32 v68, v68
	v_sub_f32_e32 v111, v111, v70
	v_exp_f32_e32 v111, v111
	v_sub_f32_e32 v64, v64, v70
	v_exp_f32_e32 v128, v64
	v_sub_f32_e32 v65, v65, v70
	v_exp_f32_e32 v65, v65
	v_add_f32_e32 v110, v68, v171
	v_add_f32_e32 v110, v111, v110
	v_add_f32_e32 v64, v128, v110
	v_add_f32_e32 v110, v65, v64
	v_cvt_pk_bf16_f32 v64, v68, v111
	v_sub_f32_e32 v68, v108, v70
	v_exp_f32_e32 v68, v68
	v_sub_f32_e32 v109, v109, v70
	v_exp_f32_e32 v109, v109
	v_sub_f32_e32 v66, v66, v70
	v_add_f32_e32 v108, v68, v110
	v_exp_f32_e32 v110, v66
	v_sub_f32_e32 v67, v67, v70
	v_exp_f32_e32 v67, v67
	v_add_f32_e32 v108, v109, v108
	v_add_f32_e32 v66, v110, v108
	v_sub_f32_e32 v111, v177, v70
	v_add_f32_e32 v108, v67, v66
	v_cvt_pk_bf16_f32 v66, v68, v109
	v_sub_f32_e32 v68, v178, v70
	v_sub_f32_e32 v109, v179, v70
	v_exp_f32_e32 v68, v68
	v_exp_f32_e32 v109, v109
	v_cvt_pk_bf16_f32 v67, v110, v67
	v_sub_f32_e32 v110, v176, v70
	v_exp_f32_e32 v110, v110
	v_add_f32_e32 v108, v68, v108
	v_exp_f32_e32 v111, v111
	v_cvt_pk_bf16_f32 v178, v68, v109
	v_sub_f32_e32 v68, v182, v70
	v_add_f32_e32 v108, v109, v108
	v_exp_f32_e32 v68, v68
	v_sub_f32_e32 v109, v183, v70
	v_exp_f32_e32 v109, v109
	v_add_f32_e32 v108, v110, v108
	v_add_f32_e32 v108, v111, v108
	v_cvt_pk_bf16_f32 v179, v110, v111
	v_sub_f32_e32 v110, v184, v70
	v_sub_f32_e32 v111, v185, v70
	v_add_f32_e32 v108, v68, v108
	v_exp_f32_e32 v110, v110
	v_exp_f32_e32 v111, v111
	v_add_f32_e32 v108, v109, v108
	v_cvt_pk_bf16_f32 v182, v68, v109
	v_sub_f32_e32 v68, v186, v70
	v_sub_f32_e32 v109, v187, v70
	v_exp_f32_e32 v68, v68
	v_exp_f32_e32 v109, v109
	v_add_f32_e32 v108, v110, v108
	v_cvt_pk_bf16_f32 v183, v110, v111
	v_sub_f32_e32 v110, v188, v70
	v_add_f32_e32 v108, v111, v108
	v_exp_f32_e32 v110, v110
	v_sub_f32_e32 v111, v189, v70
	v_add_f32_e32 v108, v68, v108
	v_exp_f32_e32 v111, v111
	v_cvt_pk_bf16_f32 v184, v68, v109
	v_sub_f32_e32 v68, v190, v70
	v_add_f32_e32 v108, v109, v108
	v_exp_f32_e32 v68, v68
	v_sub_f32_e32 v109, v191, v70
	v_exp_f32_e32 v109, v109
	ds_read_b64_tr_b16 v[190:191], v150 offset:55296
	v_add_f32_e32 v108, v110, v108
	v_add_f32_e32 v108, v111, v108
	v_add_f32_e32 v108, v68, v108
	v_add_f32_e32 v108, v109, v108
	v_cvt_pk_bf16_f32 v186, v68, v109
	v_sub_f32_e32 v68, v194, v70
	v_sub_f32_e32 v109, v195, v70
	ds_read_b64_tr_b16 v[194:195], v150 offset:57600
	v_cvt_pk_bf16_f32 v180, v135, v180
	v_cvt_pk_bf16_f32 v185, v110, v111
	v_sub_f32_e32 v110, v192, v70
	v_sub_f32_e32 v111, v193, v70
	s_waitcnt lgkmcnt(1)
	v_mfma_f32_16x16x16_bf16 v[190:193], v[190:191], v[180:181], 0
	v_cvt_pk_bf16_f32 v65, v128, v65
	v_exp_f32_e32 v110, v110
	v_exp_f32_e32 v111, v111
	s_waitcnt lgkmcnt(0)
	v_mfma_f32_16x16x16_bf16 v[190:193], v[194:195], v[64:65], v[190:193]
	ds_read_b64_tr_b16 v[194:195], v150 offset:59904
	v_add_f32_e32 v108, v110, v108
	v_exp_f32_e32 v68, v68
	s_waitcnt lgkmcnt(0)
	v_mfma_f32_16x16x16_bf16 v[190:193], v[194:195], v[66:67], v[190:193]
	ds_read_b64_tr_b16 v[194:195], v150 offset:62208
	v_exp_f32_e32 v109, v109
	v_add_f32_e32 v108, v111, v108
	s_waitcnt lgkmcnt(0)
	v_mfma_f32_16x16x16_bf16 v[190:193], v[194:195], v[178:179], v[190:193]
	ds_read_b64_tr_b16 v[194:195], v150 offset:64512
	v_cvt_pk_bf16_f32 v187, v110, v111
	v_sub_f32_e32 v110, v196, v70
	s_waitcnt lgkmcnt(0)
	v_mfma_f32_16x16x16_bf16 v[190:193], v[194:195], v[182:183], v[190:193]
	ds_read_b64_tr_b16 v[194:195], v151 offset:11520
	v_sub_f32_e32 v111, v197, v70
	v_exp_f32_e32 v110, v110
	s_waitcnt lgkmcnt(0)
	v_mfma_f32_16x16x16_bf16 v[190:193], v[194:195], v[184:185], v[190:193]
	ds_read_b64_tr_b16 v[194:195], v151 offset:13824
	v_exp_f32_e32 v111, v111
	v_add_f32_e32 v108, v68, v108
	v_cvt_pk_bf16_f32 v188, v68, v109
	v_sub_f32_e32 v68, v159, v70
	v_add_f32_e32 v108, v109, v108
	v_exp_f32_e32 v68, v68
	v_sub_f32_e32 v109, v167, v70
	v_add_f32_e32 v108, v110, v108
	v_cvt_pk_bf16_f32 v189, v110, v111
	v_exp_f32_e32 v109, v109
	v_sub_f32_e32 v110, v163, v70
	v_add_f32_e32 v108, v111, v108
	v_exp_f32_e32 v111, v110
	v_sub_f32_e32 v106, v106, v70
	s_waitcnt lgkmcnt(0)
	v_mfma_f32_16x16x16_bf16 v[190:193], v[194:195], v[186:187], v[190:193]
	ds_read_b64_tr_b16 v[194:195], v151 offset:16128
	v_exp_f32_e32 v106, v106
	v_add_f32_e32 v108, v68, v108
	v_add_f32_e32 v108, v109, v108
	v_add_f32_e32 v108, v111, v108
	v_add_f32_e32 v108, v106, v108
	v_cvt_pk_bf16_f32 v110, v68, v109
	ds_bpermute_b32 v68, v224, v108
	s_waitcnt lgkmcnt(1)
	v_mfma_f32_16x16x16_bf16 v[190:193], v[194:195], v[188:189], v[190:193]
	ds_read_b64_tr_b16 v[194:195], v151 offset:18432
	v_cvt_pk_bf16_f32 v111, v111, v106
	s_waitcnt lgkmcnt(1)
	v_add_f32_e32 v68, v108, v68
	ds_bpermute_b32 v106, v225, v68
	s_waitcnt lgkmcnt(1)
	v_mfma_f32_16x16x16_bf16 v[190:193], v[194:195], v[110:111], v[190:193]
	s_waitcnt lgkmcnt(0)
	v_add_f32_e32 v106, v68, v106
	v_rcp_f32_e32 v68, v106
	v_lshl_add_u64 v[108:109], v[198:199], 0, s[96:97]
	v_mov_b64_e32 v[176:177], s[4:5]
	v_mad_u64_u32 v[176:177], s[14:15], v108, s83, v[176:177]
	v_mad_i32_i24 v177, v109, s83, v177
	v_lshl_add_u64 v[176:177], s[12:13], 1, v[176:177]
	v_lshlrev_b32_e32 v128, 1, v112
	v_pk_mul_f32 v[192:193], v[192:193], v[68:69] op_sel_hi:[1,0]
	v_pk_mul_f32 v[190:191], v[190:191], v[68:69] op_sel_hi:[1,0]
	v_lshl_add_u64 v[176:177], v[176:177], 0, v[128:129]
	v_cvt_pk_bf16_f32 v190, v190, v191
	v_cvt_pk_bf16_f32 v191, v192, v193
	global_store_dwordx2 v[176:177], v[190:191], off
	ds_read_b64_tr_b16 v[194:195], v150 offset:55328
	ds_read_b64_tr_b16 v[196:197], v150 offset:57632
	ds_read_b64_tr_b16 v[198:199], v150 offset:59936
	ds_read_b64_tr_b16 v[208:209], v150 offset:62240
	ds_read_b64_tr_b16 v[248:249], v150 offset:64544
	ds_read_b64_tr_b16 v[250:251], v151 offset:11552
	s_waitcnt lgkmcnt(5)
	v_mfma_f32_16x16x16_bf16 v[190:193], v[194:195], v[180:181], 0
	ds_read_b64_tr_b16 v[194:195], v151 offset:13856
	s_waitcnt lgkmcnt(5)
	v_mfma_f32_16x16x16_bf16 v[190:193], v[196:197], v[64:65], v[190:193]
	ds_read_b64_tr_b16 v[196:197], v151 offset:16160
	s_waitcnt lgkmcnt(5)
	v_mfma_f32_16x16x16_bf16 v[190:193], v[198:199], v[66:67], v[190:193]
	ds_read_b64_tr_b16 v[198:199], v151 offset:18464
	s_waitcnt lgkmcnt(5)
	v_mfma_f32_16x16x16_bf16 v[190:193], v[208:209], v[178:179], v[190:193]
	ds_read_b64_tr_b16 v[208:209], v150 offset:55360
	s_waitcnt lgkmcnt(5)
	v_mfma_f32_16x16x16_bf16 v[190:193], v[248:249], v[182:183], v[190:193]
	ds_read_b64_tr_b16 v[248:249], v150 offset:57664
	s_waitcnt lgkmcnt(5)
	v_mfma_f32_16x16x16_bf16 v[190:193], v[250:251], v[184:185], v[190:193]
	ds_read_b64_tr_b16 v[250:251], v150 offset:59968
	s_waitcnt lgkmcnt(5)
	v_mfma_f32_16x16x16_bf16 v[190:193], v[194:195], v[186:187], v[190:193]
	ds_read_b64_tr_b16 v[194:195], v150 offset:62272
	s_waitcnt lgkmcnt(5)
	v_mfma_f32_16x16x16_bf16 v[190:193], v[196:197], v[188:189], v[190:193]
	ds_read_b64_tr_b16 v[196:197], v150 offset:64576
	s_waitcnt lgkmcnt(5)
	v_mfma_f32_16x16x16_bf16 v[190:193], v[198:199], v[110:111], v[190:193]
	ds_read_b64_tr_b16 v[198:199], v151 offset:11584
	s_waitcnt lgkmcnt(5)
	v_mfma_f32_16x16x16_bf16 v[244:247], v[208:209], v[180:181], 0
	ds_read_b64_tr_b16 v[208:209], v151 offset:13888
	s_waitcnt lgkmcnt(5)
	v_mfma_f32_16x16x16_bf16 v[244:247], v[248:249], v[64:65], v[244:247]
	ds_read_b64_tr_b16 v[248:249], v151 offset:16192
	s_waitcnt lgkmcnt(5)
	v_mfma_f32_16x16x16_bf16 v[244:247], v[250:251], v[66:67], v[244:247]
	ds_read_b64_tr_b16 v[250:251], v151 offset:18496
	s_waitcnt lgkmcnt(5)
	v_mfma_f32_16x16x16_bf16 v[244:247], v[194:195], v[178:179], v[244:247]
	ds_read_b64_tr_b16 v[194:195], v150 offset:55392
	s_waitcnt lgkmcnt(5)
	v_mfma_f32_16x16x16_bf16 v[244:247], v[196:197], v[182:183], v[244:247]
	ds_read_b64_tr_b16 v[196:197], v150 offset:57696
	v_pk_mul_f32 v[192:193], v[192:193], v[68:69] op_sel_hi:[1,0]
	v_pk_mul_f32 v[190:191], v[190:191], v[68:69] op_sel_hi:[1,0]
	v_cvt_pk_bf16_f32 v190, v190, v191
	v_cvt_pk_bf16_f32 v191, v192, v193
	global_store_dwordx2 v[176:177], v[190:191], off offset:32
	s_waitcnt lgkmcnt(5)
	v_mfma_f32_16x16x16_bf16 v[244:247], v[198:199], v[184:185], v[244:247]
	ds_read_b64_tr_b16 v[198:199], v150 offset:60000
	s_waitcnt lgkmcnt(5)
	v_mfma_f32_16x16x16_bf16 v[244:247], v[208:209], v[186:187], v[244:247]
	ds_read_b64_tr_b16 v[208:209], v150 offset:62304
	s_waitcnt lgkmcnt(5)
	v_mfma_f32_16x16x16_bf16 v[244:247], v[248:249], v[188:189], v[244:247]
	ds_read_b64_tr_b16 v[248:249], v150 offset:64608
	s_waitcnt lgkmcnt(5)
	v_mfma_f32_16x16x16_bf16 v[244:247], v[250:251], v[110:111], v[244:247]
	ds_read_b64_tr_b16 v[250:251], v151 offset:11616
	s_waitcnt lgkmcnt(5)
	v_mfma_f32_16x16x16_bf16 v[190:193], v[194:195], v[180:181], 0
	ds_read_b64_tr_b16 v[194:195], v151 offset:13920
	s_waitcnt lgkmcnt(5)
	v_mfma_f32_16x16x16_bf16 v[190:193], v[196:197], v[64:65], v[190:193]
	ds_read_b64_tr_b16 v[196:197], v151 offset:16224
	s_waitcnt lgkmcnt(5)
	v_mfma_f32_16x16x16_bf16 v[190:193], v[198:199], v[66:67], v[190:193]
	ds_read_b64_tr_b16 v[198:199], v151 offset:18528
	s_waitcnt lgkmcnt(5)
	v_mfma_f32_16x16x16_bf16 v[190:193], v[208:209], v[178:179], v[190:193]
	s_waitcnt lgkmcnt(4)
	v_mfma_f32_16x16x16_bf16 v[190:193], v[248:249], v[182:183], v[190:193]
	v_pk_mul_f32 v[246:247], v[246:247], v[68:69] op_sel_hi:[1,0]
	v_pk_mul_f32 v[244:245], v[244:245], v[68:69] op_sel_hi:[1,0]
	v_cvt_pk_bf16_f32 v244, v244, v245
	v_cvt_pk_bf16_f32 v245, v246, v247
	global_store_dwordx2 v[176:177], v[244:245], off offset:64
	s_waitcnt lgkmcnt(3)
	v_mfma_f32_16x16x16_bf16 v[190:193], v[250:251], v[184:185], v[190:193]
	s_waitcnt lgkmcnt(2)
	v_mfma_f32_16x16x16_bf16 v[190:193], v[194:195], v[186:187], v[190:193]
	s_waitcnt lgkmcnt(1)
	v_mfma_f32_16x16x16_bf16 v[190:193], v[196:197], v[188:189], v[190:193]
	s_waitcnt lgkmcnt(0)
	v_mfma_f32_16x16x16_bf16 v[190:193], v[198:199], v[110:111], v[190:193]
	s_nop 7
	v_pk_mul_f32 v[192:193], v[192:193], v[68:69] op_sel_hi:[1,0]
	v_pk_mul_f32 v[190:191], v[190:191], v[68:69] op_sel_hi:[1,0]
	v_cvt_pk_bf16_f32 v190, v190, v191
	v_cvt_pk_bf16_f32 v191, v192, v193
	global_store_dwordx2 v[176:177], v[190:191], off offset:96
	s_and_saveexec_b64 s[14:15], s[40:41]
	s_cbranch_execz .LBB0_280
	v_log_f32_e32 v64, v106
	s_nop 0
	v_add_f32_e32 v64, v70, v64
	v_mul_f32_e32 v66, 0x3f317218, v64
	v_mad_u64_u32 v[64:65], s[38:39], v108, 24, s[10:11]
	v_mad_i32_i24 v65, v109, 24, v65
	v_lshl_add_u64 v[64:65], s[0:1], 2, v[64:65]
	global_store_dword v[64:65], v66, off

.LBB0_300:
	s_mov_b32 s2, 0xff61b1e6
	v_max3_f32 v76, v110, s2, v106
	v_max3_f32 v76, v76, v65, v64
	v_max3_f32 v76, v76, v108, v109
	v_max3_f32 v76, v76, v66, v67
	v_max3_f32 v76, v76, v70, v71
	v_max3_f32 v76, v76, v68, v69
	v_max3_f32 v76, v76, v74, v75
	v_max3_f32 v76, v76, v72, v73
	v_max3_f32 v76, v76, v82, v83
	v_max3_f32 v76, v76, v80, v81
	v_max3_f32 v76, v76, v86, v87
	v_max3_f32 v76, v76, v84, v85
	v_max3_f32 v76, v76, v90, v91
	v_max3_f32 v76, v76, v88, v89
	v_max3_f32 v76, v76, v94, v95
	v_max3_f32 v76, v76, v92, v93
	v_add_u32_e32 v77, s25, v102
	v_max3_f32 v76, v76, v103, v101
	v_lshlrev_b32_e32 v77, s28, v77
	v_max3_f32 v76, v76, v100, v99
	v_add_u32_e32 v96, s36, v77
	ds_bpermute_b32 v77, v224, v76
	v_ashrrev_i32_e32 v97, 31, v96
	s_waitcnt lgkmcnt(0)
	v_max_f32_e32 v77, v77, v77
	v_max_f32_e32 v76, v76, v77
	ds_bpermute_b32 v77, v225, v76
	s_waitcnt lgkmcnt(0)
	v_max_f32_e32 v77, v77, v77
	v_max_f32_e32 v98, v76, v77
	v_sub_f32_e32 v76, v110, v98
	v_sub_f32_e32 v78, v106, v98
	v_exp_f32_e32 v76, v76
	v_exp_f32_e32 v78, v78
	v_sub_f32_e32 v65, v65, v98
	v_exp_f32_e32 v65, v65
	v_sub_f32_e32 v64, v64, v98
	v_exp_f32_e32 v79, v64
	v_add_f32_e32 v77, 0, v76
	v_cvt_pk_bf16_f32 v64, v76, v78
	v_sub_f32_e32 v76, v108, v98
	v_add_f32_e32 v77, v78, v77
	v_exp_f32_e32 v76, v76
	v_sub_f32_e32 v78, v109, v98
	v_add_f32_e32 v77, v65, v77
	v_exp_f32_e32 v78, v78
	v_sub_f32_e32 v66, v66, v98
	v_add_f32_e32 v77, v79, v77
	v_cvt_pk_bf16_f32 v65, v65, v79
	v_exp_f32_e32 v79, v66
	v_sub_f32_e32 v67, v67, v98
	v_exp_f32_e32 v67, v67
	v_sub_f32_e32 v70, v70, v98
	v_add_f32_e32 v77, v76, v77
	v_exp_f32_e32 v70, v70
	v_sub_f32_e32 v71, v71, v98
	v_add_f32_e32 v77, v78, v77
	v_exp_f32_e32 v71, v71
	v_sub_f32_e32 v68, v68, v98
	v_add_f32_e32 v66, v79, v77
	v_exp_f32_e32 v68, v68
	v_sub_f32_e32 v69, v69, v98
	v_add_f32_e32 v77, v67, v66
	v_exp_f32_e32 v69, v69
	v_cvt_pk_bf16_f32 v66, v76, v78
	v_add_f32_e32 v76, v70, v77
	v_add_f32_e32 v76, v71, v76
	v_add_f32_e32 v76, v68, v76
	v_add_f32_e32 v78, v69, v76
	v_cvt_pk_bf16_f32 v76, v70, v71
	v_cvt_pk_bf16_f32 v77, v68, v69
	v_sub_f32_e32 v68, v74, v98
	v_sub_f32_e32 v70, v75, v98
	v_exp_f32_e32 v68, v68
	v_exp_f32_e32 v70, v70
	v_sub_f32_e32 v71, v72, v98
	v_sub_f32_e32 v72, v73, v98
	v_exp_f32_e32 v71, v71
	v_exp_f32_e32 v72, v72
	v_add_f32_e32 v69, v68, v78
	v_cvt_pk_bf16_f32 v78, v68, v70
	v_sub_f32_e32 v68, v82, v98
	v_add_f32_e32 v69, v70, v69
	v_exp_f32_e32 v68, v68
	v_sub_f32_e32 v70, v83, v98
	v_cvt_pk_bf16_f32 v67, v79, v67
	v_add_f32_e32 v69, v71, v69
	v_cvt_pk_bf16_f32 v79, v71, v72
	v_exp_f32_e32 v70, v70
	v_sub_f32_e32 v71, v80, v98
	v_add_f32_e32 v69, v72, v69
	v_exp_f32_e32 v71, v71
	v_sub_f32_e32 v72, v81, v98
	v_exp_f32_e32 v72, v72
	v_add_f32_e32 v69, v68, v69
	v_add_f32_e32 v69, v70, v69
	v_cvt_pk_bf16_f32 v80, v68, v70
	v_sub_f32_e32 v68, v86, v98
	v_sub_f32_e32 v70, v87, v98
	v_add_f32_e32 v69, v71, v69
	v_exp_f32_e32 v68, v68
	v_exp_f32_e32 v70, v70
	v_add_f32_e32 v69, v72, v69
	v_cvt_pk_bf16_f32 v81, v71, v72
	v_sub_f32_e32 v71, v84, v98
	v_sub_f32_e32 v72, v85, v98
	v_exp_f32_e32 v71, v71
	v_exp_f32_e32 v72, v72
	v_add_f32_e32 v69, v68, v69
	v_cvt_pk_bf16_f32 v82, v68, v70
	v_sub_f32_e32 v68, v90, v98
	v_add_f32_e32 v69, v70, v69
	v_exp_f32_e32 v68, v68
	v_sub_f32_e32 v70, v91, v98
	v_add_f32_e32 v69, v71, v69
	v_cvt_pk_bf16_f32 v83, v71, v72
	v_exp_f32_e32 v70, v70
	v_sub_f32_e32 v71, v88, v98
	v_add_f32_e32 v69, v72, v69
	v_exp_f32_e32 v71, v71
	v_sub_f32_e32 v72, v89, v98
	v_exp_f32_e32 v72, v72
	ds_read_b64_tr_b16 v[88:89], v152 offset:55296
	v_add_f32_e32 v69, v68, v69
	v_add_f32_e32 v69, v70, v69
	v_add_f32_e32 v69, v71, v69
	v_add_f32_e32 v69, v72, v69
	v_cvt_pk_bf16_f32 v85, v71, v72
	v_sub_f32_e32 v71, v92, v98
	v_sub_f32_e32 v72, v93, v98
	ds_read_b64_tr_b16 v[92:93], v152 offset:57600
	s_waitcnt lgkmcnt(1)
	v_mfma_f32_16x16x16_bf16 v[88:91], v[88:89], v[64:65], 0
	v_cvt_pk_bf16_f32 v84, v68, v70
	v_sub_f32_e32 v68, v94, v98
	v_sub_f32_e32 v70, v95, v98
	s_waitcnt lgkmcnt(0)
	v_mfma_f32_16x16x16_bf16 v[88:91], v[92:93], v[66:67], v[88:91]
	ds_read_b64_tr_b16 v[92:93], v152 offset:59904
	v_exp_f32_e32 v68, v68
	v_exp_f32_e32 v70, v70
	s_waitcnt lgkmcnt(0)
	v_mfma_f32_16x16x16_bf16 v[88:91], v[92:93], v[76:77], v[88:91]
	ds_read_b64_tr_b16 v[92:93], v152 offset:62208
	v_exp_f32_e32 v71, v71
	v_exp_f32_e32 v72, v72
	s_waitcnt lgkmcnt(0)
	v_mfma_f32_16x16x16_bf16 v[88:91], v[92:93], v[78:79], v[88:91]
	ds_read_b64_tr_b16 v[92:93], v152 offset:64512
	v_add_f32_e32 v69, v68, v69
	v_cvt_pk_bf16_f32 v86, v68, v70
	s_waitcnt lgkmcnt(0)
	v_mfma_f32_16x16x16_bf16 v[88:91], v[92:93], v[80:81], v[88:91]
	ds_read_b64_tr_b16 v[92:93], v153 offset:11520
	v_sub_f32_e32 v68, v103, v98
	v_add_f32_e32 v69, v70, v69
	s_waitcnt lgkmcnt(0)
	v_mfma_f32_16x16x16_bf16 v[88:91], v[92:93], v[82:83], v[88:91]
	ds_read_b64_tr_b16 v[92:93], v153 offset:13824
	v_exp_f32_e32 v68, v68
	v_sub_f32_e32 v70, v101, v98
	v_add_f32_e32 v69, v71, v69
	v_cvt_pk_bf16_f32 v87, v71, v72
	v_exp_f32_e32 v70, v70
	v_sub_f32_e32 v71, v100, v98
	v_add_f32_e32 v69, v72, v69
	v_exp_f32_e32 v71, v71
	v_sub_f32_e32 v72, v99, v98
	s_waitcnt lgkmcnt(0)
	v_mfma_f32_16x16x16_bf16 v[88:91], v[92:93], v[84:85], v[88:91]
	ds_read_b64_tr_b16 v[92:93], v153 offset:16128
	v_exp_f32_e32 v72, v72
	v_add_f32_e32 v69, v68, v69
	v_add_f32_e32 v69, v70, v69
	v_add_f32_e32 v69, v71, v69
	v_add_f32_e32 v69, v72, v69
	v_cvt_pk_bf16_f32 v70, v68, v70
	ds_bpermute_b32 v68, v224, v69
	s_waitcnt lgkmcnt(1)
	v_mfma_f32_16x16x16_bf16 v[88:91], v[92:93], v[86:87], v[88:91]
	ds_read_b64_tr_b16 v[92:93], v153 offset:18432
	v_cvt_pk_bf16_f32 v71, v71, v72
	s_waitcnt lgkmcnt(1)
	v_add_f32_e32 v68, v69, v68
	ds_bpermute_b32 v69, v225, v68
	s_waitcnt lgkmcnt(1)
	v_mfma_f32_16x16x16_bf16 v[88:91], v[92:93], v[70:71], v[88:91]
	s_waitcnt lgkmcnt(0)
	v_add_f32_e32 v73, v68, v69
	v_rcp_f32_e32 v72, v73
	v_lshl_add_u64 v[68:69], v[96:97], 0, s[96:97]
	v_mov_b64_e32 v[74:75], s[4:5]
	v_mad_u64_u32 v[74:75], s[2:3], v68, s83, v[74:75]
	v_mad_i32_i24 v75, v69, s83, v75
	v_lshl_add_u64 v[74:75], s[12:13], 1, v[74:75]
	v_pk_mul_f32 v[90:91], v[90:91], v[72:73] op_sel_hi:[1,0]
	v_pk_mul_f32 v[88:89], v[88:89], v[72:73] op_sel_hi:[1,0]
	v_lshl_add_u64 v[74:75], v[74:75], 0, v[128:129]
	v_cvt_pk_bf16_f32 v88, v88, v89
	v_cvt_pk_bf16_f32 v89, v90, v91
	global_store_dwordx2 v[74:75], v[88:89], off
	ds_read_b64_tr_b16 v[92:93], v152 offset:55328
	ds_read_b64_tr_b16 v[94:95], v152 offset:57632
	ds_read_b64_tr_b16 v[96:97], v152 offset:59936
	ds_read_b64_tr_b16 v[104:105], v152 offset:62240
	ds_read_b64_tr_b16 v[106:107], v152 offset:64544
	ds_read_b64_tr_b16 v[108:109], v153 offset:11552
	ds_read_b64_tr_b16 v[110:111], v153 offset:13856
	ds_read_b64_tr_b16 v[176:177], v153 offset:16160
	s_waitcnt lgkmcnt(7)
	v_mfma_f32_16x16x16_bf16 v[88:91], v[92:93], v[64:65], 0
	ds_read_b64_tr_b16 v[92:93], v153 offset:18464
	s_waitcnt lgkmcnt(7)
	v_mfma_f32_16x16x16_bf16 v[88:91], v[94:95], v[66:67], v[88:91]
	ds_read_b64_tr_b16 v[94:95], v152 offset:55360
	s_waitcnt lgkmcnt(7)
	v_mfma_f32_16x16x16_bf16 v[88:91], v[96:97], v[76:77], v[88:91]
	ds_read_b64_tr_b16 v[96:97], v152 offset:57664
	s_waitcnt lgkmcnt(7)
	v_mfma_f32_16x16x16_bf16 v[88:91], v[104:105], v[78:79], v[88:91]
	ds_read_b64_tr_b16 v[104:105], v152 offset:59968
	s_waitcnt lgkmcnt(7)
	v_mfma_f32_16x16x16_bf16 v[88:91], v[106:107], v[80:81], v[88:91]
	ds_read_b64_tr_b16 v[106:107], v152 offset:62272
	s_waitcnt lgkmcnt(7)
	v_mfma_f32_16x16x16_bf16 v[88:91], v[108:109], v[82:83], v[88:91]
	ds_read_b64_tr_b16 v[108:109], v152 offset:64576
	s_waitcnt lgkmcnt(7)
	v_mfma_f32_16x16x16_bf16 v[88:91], v[110:111], v[84:85], v[88:91]
	ds_read_b64_tr_b16 v[110:111], v153 offset:11584
	s_waitcnt lgkmcnt(7)
	v_mfma_f32_16x16x16_bf16 v[88:91], v[176:177], v[86:87], v[88:91]
	ds_read_b64_tr_b16 v[176:177], v153 offset:13888
	s_waitcnt lgkmcnt(7)
	v_mfma_f32_16x16x16_bf16 v[88:91], v[92:93], v[70:71], v[88:91]
	ds_read_b64_tr_b16 v[92:93], v153 offset:16192
	s_waitcnt lgkmcnt(7)
	v_mfma_f32_16x16x16_bf16 v[100:103], v[94:95], v[64:65], 0
	ds_read_b64_tr_b16 v[94:95], v153 offset:18496
	s_waitcnt lgkmcnt(7)
	v_mfma_f32_16x16x16_bf16 v[100:103], v[96:97], v[66:67], v[100:103]
	ds_read_b64_tr_b16 v[96:97], v152 offset:55392
	s_waitcnt lgkmcnt(7)
	v_mfma_f32_16x16x16_bf16 v[100:103], v[104:105], v[76:77], v[100:103]
	ds_read_b64_tr_b16 v[104:105], v152 offset:57696
	s_waitcnt lgkmcnt(7)
	v_mfma_f32_16x16x16_bf16 v[100:103], v[106:107], v[78:79], v[100:103]
	ds_read_b64_tr_b16 v[106:107], v152 offset:60000
	s_waitcnt lgkmcnt(7)
	v_mfma_f32_16x16x16_bf16 v[100:103], v[108:109], v[80:81], v[100:103]
	ds_read_b64_tr_b16 v[108:109], v152 offset:62304
	v_pk_mul_f32 v[90:91], v[90:91], v[72:73] op_sel_hi:[1,0]
	v_pk_mul_f32 v[88:89], v[88:89], v[72:73] op_sel_hi:[1,0]
	v_cvt_pk_bf16_f32 v88, v88, v89
	v_cvt_pk_bf16_f32 v89, v90, v91
	global_store_dwordx2 v[74:75], v[88:89], off offset:32
	s_waitcnt lgkmcnt(7)
	v_mfma_f32_16x16x16_bf16 v[100:103], v[110:111], v[82:83], v[100:103]
	ds_read_b64_tr_b16 v[110:111], v152 offset:64608
	s_waitcnt lgkmcnt(7)
	v_mfma_f32_16x16x16_bf16 v[100:103], v[176:177], v[84:85], v[100:103]
	ds_read_b64_tr_b16 v[176:177], v153 offset:11616
	s_waitcnt lgkmcnt(7)
	v_mfma_f32_16x16x16_bf16 v[100:103], v[92:93], v[86:87], v[100:103]
	ds_read_b64_tr_b16 v[92:93], v153 offset:13920
	s_waitcnt lgkmcnt(7)
	v_mfma_f32_16x16x16_bf16 v[100:103], v[94:95], v[70:71], v[100:103]
	ds_read_b64_tr_b16 v[94:95], v153 offset:16224
	s_waitcnt lgkmcnt(7)
	v_mfma_f32_16x16x16_bf16 v[88:91], v[96:97], v[64:65], 0
	ds_read_b64_tr_b16 v[96:97], v153 offset:18528
	s_waitcnt lgkmcnt(7)
	v_mfma_f32_16x16x16_bf16 v[88:91], v[104:105], v[66:67], v[88:91]
	s_waitcnt lgkmcnt(6)
	v_mfma_f32_16x16x16_bf16 v[88:91], v[106:107], v[76:77], v[88:91]
	s_waitcnt lgkmcnt(5)
	v_mfma_f32_16x16x16_bf16 v[88:91], v[108:109], v[78:79], v[88:91]
	s_waitcnt lgkmcnt(4)
	v_mfma_f32_16x16x16_bf16 v[88:91], v[110:111], v[80:81], v[88:91]
	v_pk_mul_f32 v[102:103], v[102:103], v[72:73] op_sel_hi:[1,0]
	v_pk_mul_f32 v[100:101], v[100:101], v[72:73] op_sel_hi:[1,0]
	v_cvt_pk_bf16_f32 v100, v100, v101
	v_cvt_pk_bf16_f32 v101, v102, v103
	global_store_dwordx2 v[74:75], v[100:101], off offset:64
	s_waitcnt lgkmcnt(3)
	v_mfma_f32_16x16x16_bf16 v[88:91], v[176:177], v[82:83], v[88:91]
	s_waitcnt lgkmcnt(2)
	v_mfma_f32_16x16x16_bf16 v[88:91], v[92:93], v[84:85], v[88:91]
	s_waitcnt lgkmcnt(1)
	v_mfma_f32_16x16x16_bf16 v[88:91], v[94:95], v[86:87], v[88:91]
	s_waitcnt lgkmcnt(0)
	v_mfma_f32_16x16x16_bf16 v[88:91], v[96:97], v[70:71], v[88:91]
	s_nop 7
	v_pk_mul_f32 v[90:91], v[90:91], v[72:73] op_sel_hi:[1,0]
	v_pk_mul_f32 v[88:89], v[88:89], v[72:73] op_sel_hi:[1,0]
	v_cvt_pk_bf16_f32 v88, v88, v89
	v_cvt_pk_bf16_f32 v89, v90, v91
	global_store_dwordx2 v[74:75], v[88:89], off offset:96
	s_and_saveexec_b64 s[2:3], s[40:41]
	s_cbranch_execz .LBB0_249
	v_log_f32_e32 v64, v73
	s_nop 0
	v_add_f32_e32 v64, v98, v64
	v_mul_f32_e32 v66, 0x3f317218, v64
	v_mad_u64_u32 v[64:65], s[6:7], v68, 24, s[10:11]
	v_mad_i32_i24 v65, v69, 24, v65
	v_lshl_add_u64 v[64:65], s[0:1], 2, v[64:65]
	global_store_dword v[64:65], v66, off
	s_branch .LBB0_249
